# v80 + P2 step 3: k_dec^T outputs produced by waves 3-7 during the inverse-level slots, q_dec-only loop, batched forward substitution on wave 0
# speedup vs baseline: 1.0071x; 1.0040x over previous
; __device__ __forceinline__ u32x4 pack8(f32x4 v0, f32x4 v1) { u32x4 w; w.x = cvt_pk_bf16(v0[0], v0[1]); w.y = cvt_pk_bf16(v0[2], v0[3]); w.z = cvt_pk_bf16(v1[0], v1[1]); w.w = cvt_pk_bf16(v1[2], v1[3]); return w; }
; #define LAS __attribute__((address_space(3)))
; __device__ __forceinline__ int frag_off(int row, int k, int ksteps) { return ((row >> 4) * ksteps + (k >> 5)) * 512 + (((k >> 3) & 3) * 16 + (row & 15)) * 8 + (k & 7); }
; template <int SKIP>
; __device__ __forceinline__ void p2_chunk_prep_fast(Frame& F, const Args& a) {
;     ...
;             bf16_t *oQD = QD + (size_t)cu * 8192, *oKDT = KDT + (size_t)cu * 8192;
;             for (int idx = tid - 64; idx < 2048; idx += 448) {
;                 if (idx < 1024) { const int i = idx >> 4, d8 = (idx & 15) * 8; pg8::f32x4 x0, x1; pg8::unpack8(*(const LAS pg8::u32x4*)(L + L_QS + i * QS_LD + d8 * 2), x0, x1);
;                     const float e = __expf(gc[i]); *(pg8::u32x4*)(oQD + frag_off(i, d8, 4)) = pg8::pack8(x0 * e, x1 * e); }
;                 else { const int id = idx - 1024, d = id >> 3, i8 = (id & 7) * 8; pg8::f32x4 x0, x1; pg8::unpack8(*(const LAS pg8::u32x4*)(L + L_KT + ktoff(d, i8 >> 3)), x0, x1);
; #pragma unroll
;                     for (int j = 0; j < 4; ++j) { x0[j] *= __expf(gl - gc[i8 + j]); x1[j] *= __expf(gl - gc[i8 + 4 + j]); }
;                     *(pg8::u32x4*)(oKDT + frag_off(d, i8, 2)) = pg8::pack8(x0, x1); }
;             }
;             if (tid == 64) GL[cu] = __expf(gl);
.LBB0_699:
	s_or_b64 exec, exec, s[94:95]
	s_movk_i32 s94, 0x23f
	v_cmp_lt_i32_e32 vcc, s94, v48
	v_add_u32_e32 v46, 0x1c0, v46
	s_or_b64 s[92:93], vcc, s[92:93]
	v_add_u32_e32 v47, 0xe00, v47
	s_andn2_b64 exec, exec, s[92:93]
	s_cbranch_execz .LBB0_704

; #define LAS __attribute__((address_space(3)))
; template <int SKIP>
; __device__ __forceinline__ void p2_chunk_prep_fast(Frame& F, const Args& a) {
;     ...
;         if (SKIP & 4) {} else if (w == 0) {
;             const int ab = fq, c = fr; float t[16];
; #pragma unroll
;             for (int r = 0; r < 16; ++r) { float s = (r == c) ? 1.f : 0.f;
; #pragma unroll
;                 for (int m4 = 0; m4 < (r + 3) / 4; ++m4) { const f32x4 av = *(const LAS f32x4*)(Am + (16 * ab + r) * AM_LD + 16 * ab + 4 * m4);
; #pragma unroll
;                     for (int j = 0; j < 4; ++j) if (4 * m4 + j < r) s -= av[j] * t[4 * m4 + j]; }
;                 t[r] = s; Tm[(16 * ab + r) * AM_LD + 16 * ab + c] = s; }
.LBB0_707:
	s_and_b64 vcc, exec, s[6:7]
	s_cbranch_vccz .LBB0_709
	v_lshlrev_b32_e32 v62, 2, v66
	v_mul_lo_u32 v63, v66, s28
	v_add3_u32 v65, s29, v62, v63
	v_add3_u32 v71, s60, v62, v70
	v_add_u32_e32 v71, v71, v63
	v_add_u32_e32 v72, 0x440, v71
	v_add_u32_e32 v73, 0x880, v71
	v_add_u32_e32 v74, 0xcc0, v71
	ds_read_b128 v[84:87], v65 offset:272
	ds_read_b128 v[88:91], v65 offset:544
	ds_read_b128 v[92:95], v65 offset:816
	ds_read_b128 v[96:99], v65 offset:1088
	ds_read_b128 v[100:103], v65 offset:1360
	ds_read_b128 v[120:123], v65 offset:1632
	ds_read_b128 v[124:127], v65 offset:1904
	ds_read_b128 v[128:131], v65 offset:2176
	ds_read_b128 v[132:135], v65 offset:2448
	ds_read_b128 v[136:139], v65 offset:2720
	ds_read_b128 v[140:143], v65 offset:2992
	ds_read_b128 v[144:147], v65 offset:3264
	ds_read_b128 v[148:151], v65 offset:3536
	ds_read_b128 v[152:155], v65 offset:3808
	ds_read_b128 v[160:163], v65 offset:4080
	ds_read_b128 v[164:167], v65 offset:1376
	ds_read_b128 v[168:171], v65 offset:1648
	ds_read_b128 v[172:175], v65 offset:1920
	ds_read_b128 v[176:179], v65 offset:2192
	ds_read_b128 v[180:183], v65 offset:2464
	ds_read_b128 v[184:187], v65 offset:2736
	ds_read_b128 v[188:191], v65 offset:3008
	ds_read_b128 v[192:195], v65 offset:3280
	ds_read_b128 v[196:199], v65 offset:3552
	ds_read_b128 v[200:203], v65 offset:3824
	ds_read_b128 v[204:207], v65 offset:4096
	v_cmp_eq_u32_e64 s[88:89], 0, v83
	v_cmp_eq_u32_e64 s[90:91], 1, v83
	v_cmp_eq_u32_e64 s[92:93], 2, v83
	v_cmp_eq_u32_e64 s[94:95], 3, v83
	v_cndmask_b32_e64 v46, 0, 1.0, s[88:89]
	v_cmp_eq_u32_e64 s[88:89], 4, v83
	v_cndmask_b32_e64 v47, 0, 1.0, s[90:91]
	v_cmp_eq_u32_e64 s[90:91], 5, v83
	v_cndmask_b32_e64 v48, 0, 1.0, s[92:93]
	v_cmp_eq_u32_e64 s[92:93], 6, v83
	v_cndmask_b32_e64 v49, 0, 1.0, s[94:95]
	v_cmp_eq_u32_e64 s[94:95], 7, v83
	v_cndmask_b32_e64 v50, 0, 1.0, s[88:89]
	v_cmp_eq_u32_e64 s[88:89], 8, v83
	v_cndmask_b32_e64 v51, 0, 1.0, s[90:91]
	v_cmp_eq_u32_e64 s[90:91], 9, v83
	v_cndmask_b32_e64 v52, 0, 1.0, s[92:93]
	v_cmp_eq_u32_e64 s[92:93], 10, v83
	v_cndmask_b32_e64 v53, 0, 1.0, s[94:95]
	v_cmp_eq_u32_e64 s[94:95], 11, v83
	v_cndmask_b32_e64 v54, 0, 1.0, s[88:89]
	v_cmp_eq_u32_e64 s[88:89], 12, v83
	v_cndmask_b32_e64 v55, 0, 1.0, s[90:91]
	v_cmp_eq_u32_e64 s[90:91], 13, v83
	v_cndmask_b32_e64 v56, 0, 1.0, s[92:93]
	v_cmp_eq_u32_e64 s[92:93], 14, v83
	v_cndmask_b32_e64 v57, 0, 1.0, s[94:95]
	v_cmp_eq_u32_e64 s[94:95], 15, v83
	v_cndmask_b32_e64 v58, 0, 1.0, s[88:89]
	s_nop 0
	v_cndmask_b32_e64 v59, 0, 1.0, s[90:91]
	s_nop 0
	v_cndmask_b32_e64 v60, 0, 1.0, s[92:93]
	s_nop 0
	v_cndmask_b32_e64 v61, 0, 1.0, s[94:95]
	s_waitcnt lgkmcnt(11)
	ds_read_b128 v[208:211], v65 offset:2480
	ds_read_b128 v[212:215], v65 offset:2752
	ds_read_b128 v[216:219], v65 offset:3024
	ds_read_b128 v[220:223], v65 offset:3296
	ds_read_b128 v[224:227], v65 offset:3568
	ds_read_b128 v[228:231], v65 offset:3840
	ds_read_b128 v[232:235], v65 offset:4112
	ds_read_b128 v[236:239], v65 offset:3584
	ds_read_b128 v[240:243], v65 offset:3856
	ds_read_b128 v[244:247], v65 offset:4128
	v_fma_f32 v47, -v84, v46, v47
	v_fma_f32 v48, -v88, v46, v48
	v_fma_f32 v49, -v92, v46, v49
	v_fma_f32 v50, -v96, v46, v50
	v_fma_f32 v51, -v100, v46, v51
	v_fma_f32 v52, -v120, v46, v52
	v_fma_f32 v53, -v124, v46, v53
	v_fma_f32 v54, -v128, v46, v54
	v_fma_f32 v55, -v132, v46, v55
	v_fma_f32 v56, -v136, v46, v56
	v_fma_f32 v57, -v140, v46, v57
	v_fma_f32 v58, -v144, v46, v58
	v_fma_f32 v59, -v148, v46, v59
	v_fma_f32 v60, -v152, v46, v60
	v_fma_f32 v61, -v160, v46, v61
	v_fma_f32 v48, -v89, v47, v48
	v_fma_f32 v49, -v93, v47, v49
	v_fma_f32 v50, -v97, v47, v50
	v_fma_f32 v51, -v101, v47, v51
	v_fma_f32 v52, -v121, v47, v52
	v_fma_f32 v53, -v125, v47, v53
	v_fma_f32 v54, -v129, v47, v54
	v_fma_f32 v55, -v133, v47, v55
	v_fma_f32 v56, -v137, v47, v56
	v_fma_f32 v57, -v141, v47, v57
	v_fma_f32 v58, -v145, v47, v58
	v_fma_f32 v59, -v149, v47, v59
	v_fma_f32 v60, -v153, v47, v60
	v_fma_f32 v61, -v161, v47, v61
	v_fma_f32 v49, -v94, v48, v49
	v_fma_f32 v50, -v98, v48, v50
	v_fma_f32 v51, -v102, v48, v51
	v_fma_f32 v52, -v122, v48, v52
	v_fma_f32 v53, -v126, v48, v53
	v_fma_f32 v54, -v130, v48, v54
	v_fma_f32 v55, -v134, v48, v55
	v_fma_f32 v56, -v138, v48, v56
	v_fma_f32 v57, -v142, v48, v57
	v_fma_f32 v58, -v146, v48, v58
	v_fma_f32 v59, -v150, v48, v59
	v_fma_f32 v60, -v154, v48, v60
	v_fma_f32 v61, -v162, v48, v61
	v_fma_f32 v50, -v99, v49, v50
	v_fma_f32 v51, -v103, v49, v51
	v_fma_f32 v52, -v123, v49, v52
	v_fma_f32 v53, -v127, v49, v53
	v_fma_f32 v54, -v131, v49, v54
	v_fma_f32 v55, -v135, v49, v55
	v_fma_f32 v56, -v139, v49, v56
	v_fma_f32 v57, -v143, v49, v57
	v_fma_f32 v58, -v147, v49, v58
	v_fma_f32 v59, -v151, v49, v59
	v_fma_f32 v60, -v155, v49, v60
	v_fma_f32 v61, -v163, v49, v61
	s_waitcnt lgkmcnt(10)
	v_fma_f32 v51, -v164, v50, v51
	v_fma_f32 v52, -v168, v50, v52
	v_fma_f32 v53, -v172, v50, v53
	v_fma_f32 v54, -v176, v50, v54
	v_fma_f32 v55, -v180, v50, v55
	v_fma_f32 v56, -v184, v50, v56
	v_fma_f32 v57, -v188, v50, v57
	v_fma_f32 v58, -v192, v50, v58
	v_fma_f32 v59, -v196, v50, v59
	v_fma_f32 v60, -v200, v50, v60
	v_fma_f32 v61, -v204, v50, v61
	v_fma_f32 v52, -v169, v51, v52
	v_fma_f32 v53, -v173, v51, v53
	v_fma_f32 v54, -v177, v51, v54
	v_fma_f32 v55, -v181, v51, v55
	v_fma_f32 v56, -v185, v51, v56
	v_fma_f32 v57, -v189, v51, v57
	v_fma_f32 v58, -v193, v51, v58
	v_fma_f32 v59, -v197, v51, v59
	v_fma_f32 v60, -v201, v51, v60
	v_fma_f32 v61, -v205, v51, v61
	v_fma_f32 v53, -v174, v52, v53
	v_fma_f32 v54, -v178, v52, v54
	v_fma_f32 v55, -v182, v52, v55
	v_fma_f32 v56, -v186, v52, v56
	v_fma_f32 v57, -v190, v52, v57
	v_fma_f32 v58, -v194, v52, v58
	v_fma_f32 v59, -v198, v52, v59
	v_fma_f32 v60, -v202, v52, v60
	v_fma_f32 v61, -v206, v52, v61
	v_fma_f32 v54, -v179, v53, v54
	v_fma_f32 v55, -v183, v53, v55
	v_fma_f32 v56, -v187, v53, v56
	v_fma_f32 v57, -v191, v53, v57
	v_fma_f32 v58, -v195, v53, v58
	v_fma_f32 v59, -v199, v53, v59
	v_fma_f32 v60, -v203, v53, v60
	v_fma_f32 v61, -v207, v53, v61
	s_waitcnt lgkmcnt(3)
; #define LAS __attribute__((address_space(3)))
; template <int SKIP>
; __device__ __forceinline__ void p2_chunk_prep_fast(Frame& F, const Args& a) {
;     ...
;             for (int r = 0; r < 16; ++r) { float s = (r == c) ? 1.f : 0.f;
; #pragma unroll
;                 for (int m4 = 0; m4 < (r + 3) / 4; ++m4) { const f32x4 av = *(const LAS f32x4*)(Am + (16 * ab + r) * AM_LD + 16 * ab + 4 * m4);
; #pragma unroll
;                     for (int j = 0; j < 4; ++j) if (4 * m4 + j < r) s -= av[j] * t[4 * m4 + j]; }
;                 t[r] = s; Tm[(16 * ab + r) * AM_LD + 16 * ab + c] = s; }
;         } else {
;             bf16_t *oQD = QD + (size_t)cu * 8192, *oKDT = KDT + (size_t)cu * 8192;
;             for (int idx = tid - 64; idx < 2048; idx += 448) {
;                 if (idx < 1024) { const int i = idx >> 4, d8 = (idx & 15) * 8; pg8::f32x4 x0, x1; pg8::unpack8(*(const LAS pg8::u32x4*)(L + L_QS + i * QS_LD + d8 * 2), x0, x1);
;                     const float e = __expf(gc[i]); *(pg8::u32x4*)(oQD + frag_off(i, d8, 4)) = pg8::pack8(x0 * e, x1 * e); }
;                 else { const int id = idx - 1024, d = id >> 3, i8 = (id & 7) * 8; pg8::f32x4 x0, x1; pg8::unpack8(*(const LAS pg8::u32x4*)(L + L_KT + ktoff(d, i8 >> 3)), x0, x1);
; #pragma unroll
;                     for (int j = 0; j < 4; ++j) { x0[j] *= __expf(gl - gc[i8 + j]); x1[j] *= __expf(gl - gc[i8 + 4 + j]); }
;                     *(pg8::u32x4*)(oKDT + frag_off(d, i8, 2)) = pg8::pack8(x0, x1); }
;             }
;             if (tid == 64) GL[cu] = __expf(gl);
;         }
;         __syncthreads();
; #pragma unroll
;         for (int dd = 1; dd < 4; ++dd) {
;             if (w < 4 - dd && !(SKIP & 8)) {
;                 const int bb = w, ab = w + dd;
;                 f32x4 acc = (f32x4){0.f, 0.f, 0.f, 0.f};
;                 for (int c = bb; c < ab; ++c)
; #pragma unroll
;                     for (int ks = 0; ks < 4; ++ks) acc = __builtin_amdgcn_mfma_f32_16x16x4f32(Am[(16 * ab + fr) * AM_LD + 16 * c + 4 * ks + fq], Tm[(16 * c + 4 * ks + fq) * AM_LD + 16 * bb + fr], acc, 0, 0, 0);
;                 LAS float* Xs = (LAS float*)(L + L_XS + w * 1152);
; #pragma unroll
;                 for (int r = 0; r < 4; ++r) Xs[(4 * fq + r) * 17 + fr] = acc[r];
;                 f32x4 acc2 = (f32x4){0.f, 0.f, 0.f, 0.f};
; #pragma unroll
	v_fma_f32 v55, -v208, v54, v55
	v_fma_f32 v56, -v212, v54, v56
	v_fma_f32 v57, -v216, v54, v57
	v_fma_f32 v58, -v220, v54, v58
	v_fma_f32 v59, -v224, v54, v59
	v_fma_f32 v60, -v228, v54, v60
	v_fma_f32 v61, -v232, v54, v61
	v_fma_f32 v56, -v213, v55, v56
	v_fma_f32 v57, -v217, v55, v57
	v_fma_f32 v58, -v221, v55, v58
	v_fma_f32 v59, -v225, v55, v59
	v_fma_f32 v60, -v229, v55, v60
	v_fma_f32 v61, -v233, v55, v61
	v_fma_f32 v57, -v218, v56, v57
	v_fma_f32 v58, -v222, v56, v58
	v_fma_f32 v59, -v226, v56, v59
	v_fma_f32 v60, -v230, v56, v60
	v_fma_f32 v61, -v234, v56, v61
	v_fma_f32 v58, -v223, v57, v58
	v_fma_f32 v59, -v227, v57, v59
	v_fma_f32 v60, -v231, v57, v60
	v_fma_f32 v61, -v235, v57, v61
	s_waitcnt lgkmcnt(0)
	v_fma_f32 v59, -v236, v58, v59
	v_fma_f32 v60, -v240, v58, v60
	v_fma_f32 v61, -v244, v58, v61
	v_fma_f32 v60, -v241, v59, v60
	v_fma_f32 v61, -v245, v59, v61
	v_fma_f32 v61, -v246, v60, v61
	ds_write2_b32 v71, v46, v47 offset0:0 offset1:68
	ds_write2_b32 v71, v48, v49 offset0:136 offset1:204
	ds_write2_b32 v72, v50, v51 offset0:0 offset1:68
	ds_write2_b32 v72, v52, v53 offset0:136 offset1:204
	ds_write2_b32 v73, v54, v55 offset0:0 offset1:68
	ds_write2_b32 v73, v56, v57 offset0:136 offset1:204
	ds_write2_b32 v74, v58, v59 offset0:0 offset1:68
	ds_write2_b32 v74, v60, v61 offset0:136 offset1:204
.LBB0_709:
	v_lshl_add_u32 v47, v118, 2, s29
	v_add_u32_e32 v46, s56, v70
	v_add_u32_e32 v48, s57, v70
	s_andn2_b64 vcc, exec, s[82:83]
	v_add_u32_e32 v50, s54, v118
	s_waitcnt lgkmcnt(0)
	s_barrier
	s_cbranch_vccnz .Lkd_slot1
	v_or_b32_e32 v49, s33, v83
	v_mul_lo_u32 v49, v49, s28
	s_lshl_b32 s6, s54, 2
	v_add3_u32 v51, v47, v49, s6
	ds_read2_b32 v[56:57], v51 offset1:4
	v_mad_u64_u32 v[58:59], s[6:7], v50, s28, v[46:47]
	ds_read_b32 v52, v58
	s_waitcnt lgkmcnt(0)
	v_mfma_f32_16x16x4_f32 v[52:55], v56, v52, 0
	ds_read_b32 v56, v58 offset:1088
	s_waitcnt lgkmcnt(0)
	v_mfma_f32_16x16x4_f32 v[52:55], v57, v56, v[52:55]
	ds_read2_b32 v[56:57], v51 offset0:8 offset1:12
	ds_read_b32 v51, v58 offset:2176
	s_waitcnt lgkmcnt(0)
	v_mfma_f32_16x16x4_f32 v[52:55], v56, v51, v[52:55]
	ds_read_b32 v51, v58 offset:3264
	v_mad_u64_u32 v[58:59], s[6:7], v118, s28, v[48:49]
	s_lshl_b32 s6, s33, 2
	v_add_u32_e32 v49, s60, v49
	v_add3_u32 v49, v49, v67, s6
	s_movk_i32 s6, 0x44
	s_waitcnt lgkmcnt(0)
	v_mfma_f32_16x16x4_f32 v[52:55], v57, v51, v[52:55]
	s_nop 9
	ds_write2_b32 v58, v52, v53 offset1:17
	ds_write2_b32 v58, v54, v55 offset0:34 offset1:51
	ds_read2_b32 v[56:57], v49 offset1:4
	v_mad_u64_u32 v[58:59], s[6:7], v118, s6, v[48:49]
	ds_read2_b32 v[60:61], v58 offset1:68
	s_waitcnt lgkmcnt(0)
	v_mfma_f32_16x16x4_f32 v[52:55], v56, v60, 0
	v_mfma_f32_16x16x4_f32 v[52:55], v57, v61, v[52:55]
	ds_read2_b32 v[56:57], v49 offset0:8 offset1:12
	ds_read2_b32 v[58:59], v58 offset0:136 offset1:204
	v_add_u32_e32 v49, s33, v67
	s_waitcnt lgkmcnt(0)
	v_mfma_f32_16x16x4_f32 v[52:55], v56, v58, v[52:55]
	v_mfma_f32_16x16x4_f32 v[52:55], v57, v59, v[52:55]
	v_mad_u64_u32 v[56:57], s[6:7], v49, s28, v[46:47]
	s_nop 8
	v_xor_b32_e32 v49, 0x80000000, v52
	v_xor_b32_e32 v51, 0x80000000, v53
	v_xor_b32_e32 v52, 0x80000000, v54
	v_xor_b32_e32 v53, 0x80000000, v55
	ds_write2_b32 v56, v49, v51 offset1:68
	ds_write2_b32 v56, v52, v53 offset0:136 offset1:204
	s_branch .LBB0_711
.Lkd_slot1:
	v_subrev_u32_e32 v152, 0xc0, v0
	v_and_b32_e32 v153, 7, v152
	v_lshrrev_b32_e32 v154, 3, v152
	v_lshlrev_b32_e32 v156, 5, v153
	v_add_u32_e32 v156, 0x20500, v156
	v_mov_b32_e32 v157, 0x205fc
	ds_read_b32 v157, v157
	ds_read_b128 v[160:163], v156
	ds_read_b128 v[164:167], v156 offset:16
	v_lshrrev_b32_e32 v155, 2, v153
	v_lshlrev_b32_e32 v155, 9, v155
	v_and_b32_e32 v158, 3, v153
	v_lshl_add_u32 v155, v158, 7, v155
	v_lshrrev_b32_e32 v158, 3, v154
	v_xor_b32_e32 v158, v158, v153
	v_and_b32_e32 v158, 7, v158
	v_lshlrev_b32_e32 v158, 4, v158
	v_mad_u32_u24 v158, v154, s30, v158
	ds_read_b128 v[168:171], v158 offset:34816
	v_add_u32_e32 v159, 40, v154
	v_lshrrev_b32_e32 v172, 3, v159
	v_xor_b32_e32 v172, v172, v153
	v_and_b32_e32 v172, 7, v172
	v_lshlrev_b32_e32 v172, 4, v172
	v_mad_u32_u24 v172, v159, s30, v172
	ds_read_b128 v[176:179], v172 offset:34816
	v_readlane_b32 s88, v255, 25
	v_readlane_b32 s89, v255, 31
	s_lshl_b32 s90, s84, 14
	s_add_u32 s88, s88, s90
	s_addc_u32 s89, s89, 0
	s_waitcnt lgkmcnt(2)
	v_sub_f32_e32 v180, v157, v160
	v_mul_f32_e32 v180, 0x3fb8aa3b, v180
	v_sub_f32_e32 v181, v157, v161
	v_mul_f32_e32 v181, 0x3fb8aa3b, v181
	v_sub_f32_e32 v182, v157, v162
	v_mul_f32_e32 v182, 0x3fb8aa3b, v182
	v_sub_f32_e32 v183, v157, v163
	v_mul_f32_e32 v183, 0x3fb8aa3b, v183
	v_sub_f32_e32 v184, v157, v164
	v_mul_f32_e32 v184, 0x3fb8aa3b, v184
	v_sub_f32_e32 v185, v157, v165
	v_mul_f32_e32 v185, 0x3fb8aa3b, v185
	v_sub_f32_e32 v186, v157, v166
	v_mul_f32_e32 v186, 0x3fb8aa3b, v186
	v_sub_f32_e32 v187, v157, v167
	v_mul_f32_e32 v187, 0x3fb8aa3b, v187
	v_exp_f32_e32 v180, v180
	v_exp_f32_e32 v181, v181
	v_exp_f32_e32 v182, v182
	v_exp_f32_e32 v183, v183
	v_exp_f32_e32 v184, v184
	v_exp_f32_e32 v185, v185
	v_exp_f32_e32 v186, v186
	v_exp_f32_e32 v187, v187
	s_waitcnt lgkmcnt(1)
	v_lshrrev_b32_e32 v188, 4, v154
	v_and_b32_e32 v189, 15, v154
	v_lshlrev_b32_e32 v188, 10, v188
	v_lshl_add_u32 v188, v189, 3, v188
	v_add_lshl_u32 v188, v188, v155, 1
	v_lshlrev_b32_e32 v216, 16, v168
	v_and_b32_e32 v217, 0xffff0000, v168
	v_lshlrev_b32_e32 v218, 16, v169
	v_and_b32_e32 v219, 0xffff0000, v169
	v_lshlrev_b32_e32 v220, 16, v170
	v_and_b32_e32 v221, 0xffff0000, v170
	v_lshlrev_b32_e32 v222, 16, v171
	v_and_b32_e32 v223, 0xffff0000, v171
	v_pk_mul_f32 v[216:217], v[180:181], v[216:217]
	v_pk_mul_f32 v[218:219], v[182:183], v[218:219]
	v_pk_mul_f32 v[220:221], v[184:185], v[220:221]
	v_pk_mul_f32 v[222:223], v[186:187], v[222:223]
	s_nop 0
	v_cvt_pk_bf16_f32 v224, v216, v217
	v_cvt_pk_bf16_f32 v225, v218, v219
	v_cvt_pk_bf16_f32 v226, v220, v221
	v_cvt_pk_bf16_f32 v227, v222, v223
	s_nop 0
	global_store_dwordx4 v188, v[224:227], s[88:89]
	s_waitcnt lgkmcnt(0)
	v_lshrrev_b32_e32 v188, 4, v159
	v_and_b32_e32 v189, 15, v159
	v_lshlrev_b32_e32 v188, 10, v188
	v_lshl_add_u32 v188, v189, 3, v188
	v_add_lshl_u32 v188, v188, v155, 1
	v_lshlrev_b32_e32 v216, 16, v176
	v_and_b32_e32 v217, 0xffff0000, v176
	v_lshlrev_b32_e32 v218, 16, v177
	v_and_b32_e32 v219, 0xffff0000, v177
	v_lshlrev_b32_e32 v220, 16, v178
	v_and_b32_e32 v221, 0xffff0000, v178
	v_lshlrev_b32_e32 v222, 16, v179
	v_and_b32_e32 v223, 0xffff0000, v179
	v_pk_mul_f32 v[216:217], v[180:181], v[216:217]
	v_pk_mul_f32 v[218:219], v[182:183], v[218:219]
	v_pk_mul_f32 v[220:221], v[184:185], v[220:221]
	v_pk_mul_f32 v[222:223], v[186:187], v[222:223]
	s_nop 0
	v_cvt_pk_bf16_f32 v224, v216, v217
	v_cvt_pk_bf16_f32 v225, v218, v219
	v_cvt_pk_bf16_f32 v226, v220, v221
	v_cvt_pk_bf16_f32 v227, v222, v223
	s_nop 0
	global_store_dwordx4 v188, v[224:227], s[88:89]
; __device__ __forceinline__ u32x4 pack8(f32x4 v0, f32x4 v1) { u32x4 w; w.x = cvt_pk_bf16(v0[0], v0[1]); w.y = cvt_pk_bf16(v0[2], v0[3]); w.z = cvt_pk_bf16(v1[0], v1[1]); w.w = cvt_pk_bf16(v1[2], v1[3]); return w; }
; #define LAS __attribute__((address_space(3)))
; __device__ __forceinline__ int frag_off(int row, int k, int ksteps) { return ((row >> 4) * ksteps + (k >> 5)) * 512 + (((k >> 3) & 3) * 16 + (row & 15)) * 8 + (k & 7); }
; template <int SKIP>
; __device__ __forceinline__ void p2_chunk_prep_fast(Frame& F, const Args& a) {
;     ...
;                 else { const int id = idx - 1024, d = id >> 3, i8 = (id & 7) * 8; pg8::f32x4 x0, x1; pg8::unpack8(*(const LAS pg8::u32x4*)(L + L_KT + ktoff(d, i8 >> 3)), x0, x1);
; #pragma unroll
;                     for (int j = 0; j < 4; ++j) { x0[j] *= __expf(gl - gc[i8 + j]); x1[j] *= __expf(gl - gc[i8 + 4 + j]); }
;                     *(pg8::u32x4*)(oKDT + frag_off(d, i8, 2)) = pg8::pack8(x0, x1); }
;             }
;             if (tid == 64) GL[cu] = __expf(gl);
;         }
;         __syncthreads();
; #pragma unroll
;         for (int dd = 1; dd < 4; ++dd) {
;             if (w < 4 - dd && !(SKIP & 8)) {
;                 const int bb = w, ab = w + dd;
;                 f32x4 acc = (f32x4){0.f, 0.f, 0.f, 0.f};
;                 for (int c = bb; c < ab; ++c)
; #pragma unroll
;                     for (int ks = 0; ks < 4; ++ks) acc = __builtin_amdgcn_mfma_f32_16x16x4f32(Am[(16 * ab + fr) * AM_LD + 16 * c + 4 * ks + fq], Tm[(16 * c + 4 * ks + fq) * AM_LD + 16 * bb + fr], acc, 0, 0, 0);
;                 LAS float* Xs = (LAS float*)(L + L_XS + w * 1152);
; #pragma unroll
;                 for (int r = 0; r < 4; ++r) Xs[(4 * fq + r) * 17 + fr] = acc[r];
;                 f32x4 acc2 = (f32x4){0.f, 0.f, 0.f, 0.f};
; #pragma unroll
;                 for (int ks = 0; ks < 4; ++ks) acc2 = __builtin_amdgcn_mfma_f32_16x16x4f32(Tm[(16 * ab + fr) * AM_LD + 16 * ab + 4 * ks + fq], Xs[(4 * ks + fq) * 17 + fr], acc2, 0, 0, 0);
; #pragma unroll
;                 for (int r = 0; r < 4; ++r) Tm[(16 * ab + 4 * fq + r) * AM_LD + 16 * bb + fr] = -acc2[r];
;             }
;             __syncthreads();
.LBB0_711:
	s_andn2_b64 vcc, exec, s[2:3]
	v_add_u32_e32 v49, s33, v118
	s_waitcnt lgkmcnt(0)
	s_barrier
	s_cbranch_vccnz .Lkd_slot2
	v_or_b32_e32 v51, s10, v83
	v_mul_lo_u32 v58, v51, s28
	s_lshl_b32 s6, s54, 2
	v_add3_u32 v59, v47, v58, s6
	ds_read2_b32 v[54:55], v59 offset1:4
	v_mad_u64_u32 v[56:57], s[6:7], v50, s28, v[46:47]
	ds_read_b32 v50, v56
	s_waitcnt lgkmcnt(0)
	v_mfma_f32_16x16x4_f32 v[50:53], v54, v50, 0
	ds_read_b32 v54, v56 offset:1088
	s_waitcnt lgkmcnt(0)
	v_mfma_f32_16x16x4_f32 v[50:53], v55, v54, v[50:53]
	ds_read2_b32 v[54:55], v59 offset0:8 offset1:12
	ds_read_b32 v57, v56 offset:2176
	s_waitcnt lgkmcnt(0)
	v_mfma_f32_16x16x4_f32 v[50:53], v54, v57, v[50:53]
	ds_read_b32 v54, v56 offset:3264
	ds_read2_b32 v[56:57], v59 offset0:16 offset1:20
	s_waitcnt lgkmcnt(1)
	v_mfma_f32_16x16x4_f32 v[50:53], v55, v54, v[50:53]
	v_mad_u64_u32 v[54:55], s[6:7], v49, s28, v[46:47]
	ds_read_b32 v55, v54
	s_waitcnt lgkmcnt(0)
	v_mfma_f32_16x16x4_f32 v[50:53], v56, v55, v[50:53]
	ds_read_b32 v55, v54 offset:1088
	s_waitcnt lgkmcnt(0)
	v_mfma_f32_16x16x4_f32 v[50:53], v57, v55, v[50:53]
	ds_read2_b32 v[56:57], v59 offset0:24 offset1:28
	ds_read_b32 v55, v54 offset:2176
	s_waitcnt lgkmcnt(0)
	v_mfma_f32_16x16x4_f32 v[50:53], v56, v55, v[50:53]
	ds_read_b32 v56, v54 offset:3264
	v_mad_u64_u32 v[54:55], s[6:7], v118, s28, v[48:49]
	s_lshl_b32 s6, s10, 2
	v_add_u32_e32 v55, s60, v58
	v_add3_u32 v60, v55, v67, s6
	s_movk_i32 s6, 0x44
	s_waitcnt lgkmcnt(0)
	v_mfma_f32_16x16x4_f32 v[50:53], v57, v56, v[50:53]
	v_mad_u64_u32 v[56:57], s[6:7], v118, s6, v[48:49]
	s_nop 8
	ds_write2_b32 v54, v50, v51 offset1:17
	ds_write2_b32 v54, v52, v53 offset0:34 offset1:51
	ds_read2_b32 v[54:55], v60 offset1:4
	ds_read2_b32 v[58:59], v56 offset1:68
	s_waitcnt lgkmcnt(0)
	v_mfma_f32_16x16x4_f32 v[50:53], v54, v58, 0
	v_mfma_f32_16x16x4_f32 v[50:53], v55, v59, v[50:53]
	ds_read2_b32 v[54:55], v60 offset0:8 offset1:12
	ds_read2_b32 v[56:57], v56 offset0:136 offset1:204
	s_waitcnt lgkmcnt(0)
	v_mfma_f32_16x16x4_f32 v[50:53], v54, v56, v[50:53]
	v_add_u32_e32 v54, s10, v67
	v_mfma_f32_16x16x4_f32 v[50:53], v55, v57, v[50:53]
	v_mad_u64_u32 v[54:55], s[6:7], v54, s28, v[46:47]
	s_nop 8
	v_xor_b32_e32 v50, 0x80000000, v50
	v_xor_b32_e32 v51, 0x80000000, v51
	v_xor_b32_e32 v52, 0x80000000, v52
	v_xor_b32_e32 v53, 0x80000000, v53
	ds_write2_b32 v54, v50, v51 offset1:68
	ds_write2_b32 v54, v52, v53 offset0:136 offset1:204
	s_branch .LBB0_713
.Lkd_slot2:
	v_readlane_b32 s88, v255, 19
	s_cmp_lt_u32 s88, 3
	s_cbranch_scc1 .LBB0_713
	v_add_u32_e32 v159, 0x50, v154
	v_lshrrev_b32_e32 v172, 3, v159
	v_xor_b32_e32 v172, v172, v153
	v_and_b32_e32 v172, 7, v172
	v_lshlrev_b32_e32 v172, 4, v172
	v_mad_u32_u24 v172, v159, s30, v172
	ds_read_b128 v[176:179], v172 offset:34816
	v_readlane_b32 s88, v255, 25
	v_readlane_b32 s89, v255, 31
	s_lshl_b32 s90, s84, 14
	s_add_u32 s88, s88, s90
	s_addc_u32 s89, s89, 0
	s_waitcnt lgkmcnt(0)
	v_lshrrev_b32_e32 v188, 4, v159
	v_and_b32_e32 v189, 15, v159
	v_lshlrev_b32_e32 v188, 10, v188
	v_lshl_add_u32 v188, v189, 3, v188
	v_add_lshl_u32 v188, v188, v155, 1
	v_lshlrev_b32_e32 v216, 16, v176
	v_and_b32_e32 v217, 0xffff0000, v176
	v_lshlrev_b32_e32 v218, 16, v177
	v_and_b32_e32 v219, 0xffff0000, v177
	v_lshlrev_b32_e32 v220, 16, v178
	v_and_b32_e32 v221, 0xffff0000, v178
	v_lshlrev_b32_e32 v222, 16, v179
	v_and_b32_e32 v223, 0xffff0000, v179
	v_pk_mul_f32 v[216:217], v[180:181], v[216:217]
	v_pk_mul_f32 v[218:219], v[182:183], v[218:219]
	v_pk_mul_f32 v[220:221], v[184:185], v[220:221]
	v_pk_mul_f32 v[222:223], v[186:187], v[222:223]
	s_nop 0
	v_cvt_pk_bf16_f32 v224, v216, v217
	v_cvt_pk_bf16_f32 v225, v218, v219
	v_cvt_pk_bf16_f32 v226, v220, v221
	v_cvt_pk_bf16_f32 v227, v222, v223
	s_nop 0
	global_store_dwordx4 v188, v[224:227], s[88:89]
; __device__ __forceinline__ u32x4 pack8(f32x4 v0, f32x4 v1) { u32x4 w; w.x = cvt_pk_bf16(v0[0], v0[1]); w.y = cvt_pk_bf16(v0[2], v0[3]); w.z = cvt_pk_bf16(v1[0], v1[1]); w.w = cvt_pk_bf16(v1[2], v1[3]); return w; }
; #define LAS __attribute__((address_space(3)))
; __device__ __forceinline__ int frag_off(int row, int k, int ksteps) { return ((row >> 4) * ksteps + (k >> 5)) * 512 + (((k >> 3) & 3) * 16 + (row & 15)) * 8 + (k & 7); }
; template <int SKIP>
; __device__ __forceinline__ void p2_chunk_prep_fast(Frame& F, const Args& a) {
;     ...
;                 else { const int id = idx - 1024, d = id >> 3, i8 = (id & 7) * 8; pg8::f32x4 x0, x1; pg8::unpack8(*(const LAS pg8::u32x4*)(L + L_KT + ktoff(d, i8 >> 3)), x0, x1);
; #pragma unroll
;                     for (int j = 0; j < 4; ++j) { x0[j] *= __expf(gl - gc[i8 + j]); x1[j] *= __expf(gl - gc[i8 + 4 + j]); }
;                     *(pg8::u32x4*)(oKDT + frag_off(d, i8, 2)) = pg8::pack8(x0, x1); }
;             }
;             if (tid == 64) GL[cu] = __expf(gl);
;         }
;         __syncthreads();
; #pragma unroll
;         for (int dd = 1; dd < 4; ++dd) {
;             if (w < 4 - dd && !(SKIP & 8)) {
;                 const int bb = w, ab = w + dd;
;                 f32x4 acc = (f32x4){0.f, 0.f, 0.f, 0.f};
;                 for (int c = bb; c < ab; ++c)
; #pragma unroll
;                     for (int ks = 0; ks < 4; ++ks) acc = __builtin_amdgcn_mfma_f32_16x16x4f32(Am[(16 * ab + fr) * AM_LD + 16 * c + 4 * ks + fq], Tm[(16 * c + 4 * ks + fq) * AM_LD + 16 * bb + fr], acc, 0, 0, 0);
;                 LAS float* Xs = (LAS float*)(L + L_XS + w * 1152);
; #pragma unroll
;                 for (int r = 0; r < 4; ++r) Xs[(4 * fq + r) * 17 + fr] = acc[r];
;                 f32x4 acc2 = (f32x4){0.f, 0.f, 0.f, 0.f};
; #pragma unroll
;                 for (int ks = 0; ks < 4; ++ks) acc2 = __builtin_amdgcn_mfma_f32_16x16x4f32(Tm[(16 * ab + fr) * AM_LD + 16 * ab + 4 * ks + fq], Xs[(4 * ks + fq) * 17 + fr], acc2, 0, 0, 0);
; #pragma unroll
;                 for (int r = 0; r < 4; ++r) Tm[(16 * ab + 4 * fq + r) * AM_LD + 16 * bb + fr] = -acc2[r];
;             }
;             __syncthreads();
.LBB0_713:
	s_andn2_b64 vcc, exec, s[50:51]
	s_waitcnt lgkmcnt(0)
	s_barrier
	s_cbranch_vccnz .Lkd_slot3
	v_mul_u32_u24_e32 v58, 0x110, v83
	s_lshl_b32 s6, s54, 2
	v_add3_u32 v47, v47, v58, s6
	v_add_u32_e32 v47, 0x3000, v47
	ds_read2_b32 v[54:55], v47 offset0:192 offset1:196
	v_mul_lo_u32 v59, v118, s28
	v_add_u32_e32 v56, v46, v59
	ds_read_b32 v50, v56
	s_waitcnt lgkmcnt(0)
	v_mfma_f32_16x16x4_f32 v[50:53], v54, v50, 0
	ds_read_b32 v54, v56 offset:1088
	s_waitcnt lgkmcnt(0)
	v_mfma_f32_16x16x4_f32 v[50:53], v55, v54, v[50:53]
	ds_read2_b32 v[54:55], v47 offset0:200 offset1:204
	ds_read_b32 v57, v56 offset:2176
	s_waitcnt lgkmcnt(0)
	v_mfma_f32_16x16x4_f32 v[50:53], v54, v57, v[50:53]
	ds_read_b32 v54, v56 offset:3264
	ds_read2_b32 v[56:57], v47 offset0:208 offset1:212
	s_waitcnt lgkmcnt(1)
	v_mfma_f32_16x16x4_f32 v[50:53], v55, v54, v[50:53]
	v_mad_u64_u32 v[54:55], s[6:7], v49, s28, v[46:47]
	ds_read_b32 v49, v54
	s_waitcnt lgkmcnt(0)
	v_mfma_f32_16x16x4_f32 v[50:53], v56, v49, v[50:53]
	ds_read_b32 v49, v54 offset:1088
	s_waitcnt lgkmcnt(0)
	v_mfma_f32_16x16x4_f32 v[50:53], v57, v49, v[50:53]
	ds_read2_b32 v[56:57], v47 offset0:216 offset1:220
	ds_read_b32 v49, v54 offset:2176
	s_waitcnt lgkmcnt(0)
	v_mfma_f32_16x16x4_f32 v[50:53], v56, v49, v[50:53]
	ds_read_b32 v49, v54 offset:3264
	ds_read2_b32 v[54:55], v47 offset0:224 offset1:228
	v_add_u32_e32 v56, s10, v118
	s_waitcnt lgkmcnt(1)
	v_mfma_f32_16x16x4_f32 v[50:53], v57, v49, v[50:53]
	v_mad_u64_u32 v[56:57], s[6:7], v56, s28, v[46:47]
	ds_read_b32 v49, v56
	v_readlane_b32 s6, v255, 53
	s_waitcnt lgkmcnt(0)
	v_mfma_f32_16x16x4_f32 v[50:53], v54, v49, v[50:53]
	ds_read_b32 v49, v56 offset:1088
	s_waitcnt lgkmcnt(0)
	v_mfma_f32_16x16x4_f32 v[50:53], v55, v49, v[50:53]
	ds_read2_b32 v[54:55], v47 offset0:232 offset1:236
	ds_read_b32 v47, v56 offset:2176
	v_add_u32_e32 v49, v48, v59
	s_waitcnt lgkmcnt(0)
	v_mfma_f32_16x16x4_f32 v[50:53], v54, v47, v[50:53]
	ds_read_b32 v47, v56 offset:3264
	v_add3_u32 v54, s6, v58, v67
	v_add_u32_e32 v58, 0x3000, v54
	s_movk_i32 s6, 0x44
	s_waitcnt lgkmcnt(0)
	v_mfma_f32_16x16x4_f32 v[50:53], v55, v47, v[50:53]
	v_mad_u64_u32 v[54:55], s[6:7], v118, s6, v[48:49]
	v_readlane_b32 s6, v255, 51
	s_nop 7
	ds_write2_b32 v49, v50, v51 offset1:17
	ds_write2_b32 v49, v52, v53 offset0:34 offset1:51
	ds_read2_b32 v[52:53], v58 offset0:192 offset1:196
	ds_read2_b32 v[56:57], v54 offset1:68
	v_add_u32_e32 v47, s6, v67
	v_mad_u64_u32 v[46:47], s[6:7], v47, s28, v[46:47]
	s_waitcnt lgkmcnt(0)
	v_mfma_f32_16x16x4_f32 v[48:51], v52, v56, 0
	v_mfma_f32_16x16x4_f32 v[48:51], v53, v57, v[48:51]
	ds_read2_b32 v[52:53], v58 offset0:200 offset1:204
	ds_read2_b32 v[54:55], v54 offset0:136 offset1:204
	s_waitcnt lgkmcnt(0)
	v_mfma_f32_16x16x4_f32 v[48:51], v52, v54, v[48:51]
	v_mfma_f32_16x16x4_f32 v[48:51], v53, v55, v[48:51]
	s_nop 9
	v_xor_b32_e32 v47, 0x80000000, v48
	v_xor_b32_e32 v48, 0x80000000, v49
	v_xor_b32_e32 v49, 0x80000000, v50
	v_xor_b32_e32 v50, 0x80000000, v51
	ds_write2_b32 v46, v47, v48 offset1:68
	ds_write2_b32 v46, v49, v50 offset0:136 offset1:204
	s_branch .LBB0_715
.Lkd_slot3:
	v_readlane_b32 s88, v255, 19
	s_cmp_lg_u32 s88, 3
	s_cbranch_scc1 .LBB0_715
	v_add_u32_e32 v159, 0x78, v154
	v_lshrrev_b32_e32 v172, 3, v159
	v_xor_b32_e32 v172, v172, v153
	v_and_b32_e32 v172, 7, v172
	v_lshlrev_b32_e32 v172, 4, v172
	v_mad_u32_u24 v172, v159, s30, v172
	ds_read_b128 v[176:179], v172 offset:34816
	v_readlane_b32 s88, v255, 25
	v_readlane_b32 s89, v255, 31
	s_lshl_b32 s90, s84, 14
	s_add_u32 s88, s88, s90
	s_addc_u32 s89, s89, 0
	s_waitcnt lgkmcnt(0)
	v_lshrrev_b32_e32 v188, 4, v159
	v_and_b32_e32 v189, 15, v159
	v_lshlrev_b32_e32 v188, 10, v188
	v_lshl_add_u32 v188, v189, 3, v188
	v_add_lshl_u32 v188, v188, v155, 1
	v_lshlrev_b32_e32 v216, 16, v176
	v_and_b32_e32 v217, 0xffff0000, v176
	v_lshlrev_b32_e32 v218, 16, v177
	v_and_b32_e32 v219, 0xffff0000, v177
	v_lshlrev_b32_e32 v220, 16, v178
	v_and_b32_e32 v221, 0xffff0000, v178
	v_lshlrev_b32_e32 v222, 16, v179
	v_and_b32_e32 v223, 0xffff0000, v179
	v_pk_mul_f32 v[216:217], v[180:181], v[216:217]
	v_pk_mul_f32 v[218:219], v[182:183], v[218:219]
	v_pk_mul_f32 v[220:221], v[184:185], v[220:221]
	v_pk_mul_f32 v[222:223], v[186:187], v[222:223]
	s_nop 0
	v_cvt_pk_bf16_f32 v224, v216, v217
	v_cvt_pk_bf16_f32 v225, v218, v219
	v_cvt_pk_bf16_f32 v226, v220, v221
	v_cvt_pk_bf16_f32 v227, v222, v223
	s_nop 0
	global_store_dwordx4 v188, v[224:227], s[88:89]
